# same K-fragment read relocation, pairs placed after PV MFMAs 17,18,20,21
# baseline (speedup 1.0000x reference)
.LBB0_442:
	s_mov_b32 s30, s62
	v_mov_b64_e32 v[218:219], v[96:97]
	s_mov_b32 s63, s33
	s_mov_b32 s3, s61
	v_lshl_add_u32 v206, s36, 14, v241
	ds_read_b64_tr_b16 v[196:197], v206 offset:24576
	ds_read_b64_tr_b16 v[198:199], v206 offset:25088
	v_add_f32_e32 v96, v80, v81
	v_add_f32_e32 v96, v82, v96
	v_add_f32_e32 v96, v83, v96
	v_add_f32_e32 v96, v84, v96
	v_add_f32_e32 v96, v85, v96
	v_cvt_pk_bf16_f32 v140, v80, v81
	v_cvt_pk_bf16_f32 v141, v82, v83
	v_mfma_f32_32x32x16_bf16 v[112:127], v[188:191], v[156:159], 0
	ds_read_b64_tr_b16 v[80:81], v206 offset:28672
	ds_read_b64_tr_b16 v[82:83], v206 offset:29184
	v_add_f32_e32 v96, v86, v96
	v_add_f32_e32 v96, v87, v96
	v_add_f32_e32 v96, v88, v96
	v_add_f32_e32 v128, v89, v96
	v_mfma_f32_32x32x16_bf16 v[96:111], v[180:183], v[156:159], 0
	v_cvt_pk_bf16_f32 v142, v84, v85
	v_cvt_pk_bf16_f32 v143, v86, v87
	ds_read_b64_tr_b16 v[84:85], v206 offset:25600
	ds_read_b64_tr_b16 v[86:87], v206 offset:26112
	v_add_f32_e32 v128, v90, v128
	v_add_f32_e32 v128, v91, v128
	v_add_f32_e32 v128, v92, v128
	v_add_f32_e32 v128, v93, v128
	v_cvt_pk_bf16_f32 v136, v88, v89
	v_cvt_pk_bf16_f32 v137, v90, v91
	v_mfma_f32_32x32x16_bf16 v[112:127], v[184:187], v[152:155], v[112:127]
	ds_read_b64_tr_b16 v[88:89], v206 offset:29696
	ds_read_b64_tr_b16 v[90:91], v206 offset:30208
	v_mfma_f32_32x32x16_bf16 v[96:111], v[176:179], v[152:155], v[96:111]
	v_add_f32_e32 v128, v94, v128
	v_add_f32_e32 v128, v95, v128
	v_add_f32_e32 v128, v64, v128
	v_add_f32_e32 v128, v65, v128
	v_cvt_pk_bf16_f32 v138, v92, v93
	v_cvt_pk_bf16_f32 v139, v94, v95
	ds_read_b64_tr_b16 v[92:93], v206 offset:26624
	ds_read_b64_tr_b16 v[94:95], v206 offset:27136
	v_add_f32_e32 v128, v66, v128
	v_add_f32_e32 v128, v67, v128
	v_add_f32_e32 v128, v68, v128
	v_add_f32_e32 v128, v69, v128
	v_cvt_pk_bf16_f32 v132, v64, v65
	v_cvt_pk_bf16_f32 v133, v66, v67
	v_mfma_f32_32x32x16_bf16 v[112:127], v[172:175], v[148:151], v[112:127]
	ds_read_b64_tr_b16 v[200:201], v206 offset:30720
	ds_read_b64_tr_b16 v[202:203], v206 offset:31232
	v_mfma_f32_32x32x16_bf16 v[96:111], v[168:171], v[148:151], v[96:111]
	v_add_f32_e32 v64, v70, v128
	v_add_f32_e32 v64, v71, v64
	v_add_f32_e32 v64, v72, v64
	v_add_f32_e32 v64, v73, v64
	v_cvt_pk_bf16_f32 v134, v68, v69
	v_cvt_pk_bf16_f32 v135, v70, v71
	ds_read_b64_tr_b16 v[242:243], v206 offset:27648
	ds_read_b64_tr_b16 v[244:245], v206 offset:28160
	v_add_f32_e32 v64, v74, v64
	v_add_f32_e32 v64, v75, v64
	v_add_f32_e32 v64, v76, v64
	v_add_f32_e32 v64, v77, v64
	v_cvt_pk_bf16_f32 v128, v72, v73
	v_cvt_pk_bf16_f32 v129, v74, v75
	v_mfma_f32_32x32x16_bf16 v[112:127], v[164:167], v[144:147], v[112:127]
	ds_read_b64_tr_b16 v[72:73], v206 offset:31744
	ds_read_b64_tr_b16 v[74:75], v206 offset:32256
	v_mfma_f32_32x32x16_bf16 v[96:111], v[160:163], v[144:147], v[96:111]
	v_add_f32_e32 v64, v78, v64
	v_add_f32_e32 v64, v79, v64
	v_add_f32_e32 v64, 0, v64
	v_cvt_pk_bf16_f32 v130, v76, v77
	v_cvt_pk_bf16_f32 v131, v78, v79
	v_lshl_add_u64 v[186:187], v[194:195], 0, s[4:5]
	s_mov_b64 s[34:35], 0xb622a00
	s_lshl_b32 s31, s61, 13
	v_add_f32_e32 v188, v204, v64
	v_lshl_add_u64 v[64:65], v[186:187], 0, s[34:35]
	s_add_i32 s31, s31, s58
	s_mov_b32 s33, m0
	s_mov_b32 m0, s31
	s_nop 0
	global_load_lds_dwordx4 v[64:65], off
	s_mov_b32 m0, s33
	v_lshl_add_u64 v[184:185], v[192:193], 0, s[4:5]
	s_mov_b64 s[34:35], 0xb412e00
	s_lshl_b32 s64, s62, 14
	v_lshl_add_u64 v[64:65], v[184:185], 0, s[34:35]
	s_add_i32 s31, s64, s59
	s_mov_b32 s33, m0
	s_mov_b32 m0, s31
	s_nop 0
	global_load_lds_dwordx4 v[64:65], off
	s_mov_b32 m0, s33
	s_mov_b64 s[34:35], 0xb412e80
	v_lshl_add_u64 v[64:65], v[184:185], 0, s[34:35]
	s_addk_i32 s31, 0x2000
	s_mov_b32 s33, m0
	s_mov_b32 m0, s31
	s_nop 0
	global_load_lds_dwordx4 v[64:65], off
	s_mov_b32 m0, s33
	s_waitcnt lgkmcnt(14)
	v_mfma_f32_32x32x16_bf16 v[48:63], v[140:143], v[196:199], v[48:63]
	v_exp_f32_e32 v112, v112
	v_exp_f32_e32 v113, v113
	ds_read_b64_tr_b16 v[76:77], v206 offset:32768
	ds_read_b64_tr_b16 v[78:79], v206 offset:33280
	s_waitcnt lgkmcnt(14)
	v_mfma_f32_32x32x16_bf16 v[32:47], v[140:143], v[80:83], v[32:47]
	v_exp_f32_e32 v114, v114
	v_exp_f32_e32 v115, v115
	ds_read_b64_tr_b16 v[80:81], v206 offset:36864
	ds_read_b64_tr_b16 v[82:83], v206 offset:37376
	s_waitcnt lgkmcnt(14)
	v_mfma_f32_32x32x16_bf16 v[48:63], v[136:139], v[84:87], v[48:63]
	v_exp_f32_e32 v116, v116
	v_exp_f32_e32 v117, v117
	ds_read_b64_tr_b16 v[84:85], v206 offset:33792
	ds_read_b64_tr_b16 v[86:87], v206 offset:34304
	s_waitcnt lgkmcnt(14)
	v_mfma_f32_32x32x16_bf16 v[32:47], v[136:139], v[88:91], v[32:47]
	v_exp_f32_e32 v118, v118
	v_exp_f32_e32 v119, v119
	ds_read_b64_tr_b16 v[88:89], v206 offset:37888
	ds_read_b64_tr_b16 v[90:91], v206 offset:38400
	s_waitcnt lgkmcnt(14)
	v_mfma_f32_32x32x16_bf16 v[48:63], v[132:135], v[92:95], v[48:63]
	v_exp_f32_e32 v120, v120
	v_exp_f32_e32 v121, v121
	ds_read_b64_tr_b16 v[92:93], v206 offset:34816
	ds_read_b64_tr_b16 v[94:95], v206 offset:35328
	s_waitcnt lgkmcnt(14)
	v_mfma_f32_32x32x16_bf16 v[32:47], v[132:135], v[200:203], v[32:47]
	v_exp_f32_e32 v122, v122
	v_exp_f32_e32 v123, v123
	ds_read_b64_tr_b16 v[196:197], v206 offset:38912
	ds_read_b64_tr_b16 v[198:199], v206 offset:39424
	s_waitcnt lgkmcnt(14)
	v_mfma_f32_32x32x16_bf16 v[48:63], v[128:131], v[242:245], v[48:63]
	v_exp_f32_e32 v124, v124
	v_exp_f32_e32 v125, v125
	ds_read_b64_tr_b16 v[200:201], v206 offset:35840
	ds_read_b64_tr_b16 v[202:203], v206 offset:36352
	s_waitcnt lgkmcnt(14)
	v_mfma_f32_32x32x16_bf16 v[32:47], v[128:131], v[72:75], v[32:47]
	v_exp_f32_e32 v126, v126
	v_exp_f32_e32 v127, v127
	ds_read_b64_tr_b16 v[72:73], v206 offset:39936
	ds_read_b64_tr_b16 v[74:75], v206 offset:40448
	s_waitcnt lgkmcnt(14)
	v_mfma_f32_32x32x16_bf16 v[16:31], v[140:143], v[76:79], v[16:31]
	v_exp_f32_e32 v96, v96
	v_exp_f32_e32 v97, v97
	s_lshl_b32 s31, s62, 13
	v_add_u32_e32 v160, s31, v239
	ds_read_b128 v[68:71], v160
	ds_read_b128 v[64:67], v160 offset:512
	s_waitcnt lgkmcnt(14)
	v_mfma_f32_32x32x16_bf16 v[0:15], v[140:143], v[80:83], v[0:15]
	v_exp_f32_e32 v98, v98
	v_exp_f32_e32 v99, v99
	ds_read_b128 v[180:183], v160 offset:2048
	ds_read_b128 v[176:179], v160 offset:2560
	s_waitcnt lgkmcnt(14)
	v_mfma_f32_32x32x16_bf16 v[16:31], v[136:139], v[84:87], v[16:31]
	v_exp_f32_e32 v100, v100
	v_exp_f32_e32 v101, v101
	s_waitcnt lgkmcnt(12)
	v_mfma_f32_32x32x16_bf16 v[0:15], v[136:139], v[88:91], v[0:15]
	v_exp_f32_e32 v102, v102
	v_exp_f32_e32 v103, v103
	ds_read_b128 v[172:175], v160 offset:4096
	ds_read_b128 v[168:171], v160 offset:4608
	s_waitcnt lgkmcnt(12)
	v_mfma_f32_32x32x16_bf16 v[16:31], v[132:135], v[92:95], v[16:31]
	v_exp_f32_e32 v104, v104
	v_exp_f32_e32 v105, v105
	ds_read_b128 v[164:167], v160 offset:6144
	ds_read_b128 v[160:163], v160 offset:6656
	s_waitcnt lgkmcnt(12)
	v_mfma_f32_32x32x16_bf16 v[0:15], v[132:135], v[196:199], v[0:15]
	v_exp_f32_e32 v106, v106
	v_exp_f32_e32 v107, v107
	s_waitcnt lgkmcnt(10)
	v_mfma_f32_32x32x16_bf16 v[16:31], v[128:131], v[200:203], v[16:31]
	v_exp_f32_e32 v108, v108
	v_exp_f32_e32 v109, v109
	s_waitcnt lgkmcnt(8)
	v_mfma_f32_32x32x16_bf16 v[0:15], v[128:131], v[72:75], v[0:15]
	v_exp_f32_e32 v110, v110
	v_exp_f32_e32 v111, v111
	s_waitcnt vmcnt(3) lgkmcnt(0)
	s_barrier
	s_add_i32 s33, s62, 1
	s_cmp_lg_u32 s62, 2
	s_cselect_b32 s61, s33, 0
	v_lshl_add_u32 v200, s3, 14, v241
	ds_read_b64_tr_b16 v[196:197], v200 offset:24576
	ds_read_b64_tr_b16 v[198:199], v200 offset:25088
	v_mfma_f32_32x32x16_bf16 v[80:95], v[68:71], v[156:159], 0
	v_add_f32_e32 v72, v112, v113
	v_add_f32_e32 v72, v114, v72
	v_add_f32_e32 v72, v115, v72
	v_add_f32_e32 v72, v116, v72
	v_add_f32_e32 v72, v117, v72
	v_cvt_pk_bf16_f32 v140, v112, v113
	v_cvt_pk_bf16_f32 v141, v114, v115
	ds_read_b64_tr_b16 v[112:113], v200 offset:28672
	ds_read_b64_tr_b16 v[114:115], v200 offset:29184
	v_add_f32_e32 v68, v118, v72
	v_add_f32_e32 v68, v119, v68
	v_add_f32_e32 v68, v120, v68
	v_add_f32_e32 v128, v121, v68
	v_mfma_f32_32x32x16_bf16 v[64:79], v[64:67], v[156:159], 0
	v_cvt_pk_bf16_f32 v142, v116, v117
	v_cvt_pk_bf16_f32 v143, v118, v119
	ds_read_b64_tr_b16 v[116:117], v200 offset:25600
	ds_read_b64_tr_b16 v[118:119], v200 offset:26112
	v_mfma_f32_32x32x16_bf16 v[80:95], v[180:183], v[152:155], v[80:95]
	v_add_f32_e32 v128, v122, v128
	v_add_f32_e32 v128, v123, v128
	v_add_f32_e32 v128, v124, v128
	v_add_f32_e32 v128, v125, v128
	v_cvt_pk_bf16_f32 v136, v120, v121
	v_cvt_pk_bf16_f32 v137, v122, v123
	ds_read_b64_tr_b16 v[120:121], v200 offset:29696
	ds_read_b64_tr_b16 v[122:123], v200 offset:30208
	v_mfma_f32_32x32x16_bf16 v[64:79], v[176:179], v[152:155], v[64:79]
	v_add_f32_e32 v128, v126, v128
	v_add_f32_e32 v128, v127, v128
	v_add_f32_e32 v128, v96, v128
	v_add_f32_e32 v128, v97, v128
	v_cvt_pk_bf16_f32 v138, v124, v125
	v_cvt_pk_bf16_f32 v139, v126, v127
	ds_read_b64_tr_b16 v[124:125], v200 offset:26624
	ds_read_b64_tr_b16 v[126:127], v200 offset:27136
	v_mfma_f32_32x32x16_bf16 v[80:95], v[172:175], v[148:151], v[80:95]
	v_add_f32_e32 v128, v98, v128
	v_add_f32_e32 v128, v99, v128
	v_add_f32_e32 v128, v100, v128
	v_add_f32_e32 v128, v101, v128
	v_cvt_pk_bf16_f32 v132, v96, v97
	v_cvt_pk_bf16_f32 v133, v98, v99
	ds_read_b64_tr_b16 v[96:97], v200 offset:30720
	ds_read_b64_tr_b16 v[98:99], v200 offset:31232
	v_mfma_f32_32x32x16_bf16 v[64:79], v[168:171], v[148:151], v[64:79]
	v_add_f32_e32 v128, v102, v128
	v_add_f32_e32 v128, v103, v128
	v_add_f32_e32 v128, v104, v128
	v_add_f32_e32 v128, v105, v128
	v_cvt_pk_bf16_f32 v134, v100, v101
	v_cvt_pk_bf16_f32 v135, v102, v103
	ds_read_b64_tr_b16 v[100:101], v200 offset:27648
	ds_read_b64_tr_b16 v[102:103], v200 offset:28160
	v_mfma_f32_32x32x16_bf16 v[80:95], v[164:167], v[144:147], v[80:95]
	v_add_f32_e32 v128, v106, v128
	v_add_f32_e32 v128, v107, v128
	v_add_f32_e32 v128, v108, v128
	v_add_f32_e32 v164, v109, v128
	v_cvt_pk_bf16_f32 v128, v104, v105
	v_cvt_pk_bf16_f32 v129, v106, v107
	ds_read_b64_tr_b16 v[104:105], v200 offset:31744
	ds_read_b64_tr_b16 v[106:107], v200 offset:32256
	v_mfma_f32_32x32x16_bf16 v[64:79], v[160:163], v[144:147], v[64:79]
	v_add_f32_e32 v130, v110, v164
	v_add_f32_e32 v130, v111, v130
	v_add_f32_e32 v160, 0, v130
	v_cvt_pk_bf16_f32 v130, v108, v109
	v_cvt_pk_bf16_f32 v131, v110, v111
	s_mov_b64 s[34:35], 0xb72aa00
	v_lshl_add_u64 v[108:109], v[186:187], 0, s[34:35]
	s_add_i32 s3, s31, s58
	s_mov_b32 s31, m0
	s_mov_b32 m0, s3
	s_nop 0
	global_load_lds_dwordx4 v[108:109], off
	s_mov_b32 m0, s31
	s_mov_b64 s[34:35], 0xb51ae00
	s_lshl_b32 s31, s61, 14
	v_lshl_add_u64 v[108:109], v[184:185], 0, s[34:35]
	s_add_i32 s3, s31, s59
	s_mov_b32 s33, m0
	s_mov_b32 m0, s3
	s_nop 0
	global_load_lds_dwordx4 v[108:109], off
	s_mov_b32 m0, s33
	s_mov_b64 s[34:35], 0xb51ae80
	v_lshl_add_u64 v[108:109], v[184:185], 0, s[34:35]
	s_addk_i32 s3, 0x2000
	s_mov_b32 s33, m0
	s_mov_b32 m0, s3
	s_nop 0
	global_load_lds_dwordx4 v[108:109], off
	s_mov_b32 m0, s33
	v_add_f32_e32 v204, v188, v160
	s_add_i32 s60, s60, 2
	s_waitcnt lgkmcnt(14)
	v_mfma_f32_32x32x16_bf16 v[48:63], v[140:143], v[196:199], v[48:63]
	v_exp_f32_e32 v80, v80
	v_exp_f32_e32 v81, v81
	ds_read_b64_tr_b16 v[108:109], v200 offset:32768
	ds_read_b64_tr_b16 v[110:111], v200 offset:33280
	s_waitcnt lgkmcnt(14)
	v_mfma_f32_32x32x16_bf16 v[32:47], v[140:143], v[112:115], v[32:47]
	v_exp_f32_e32 v82, v82
	v_exp_f32_e32 v83, v83
	ds_read_b64_tr_b16 v[112:113], v200 offset:36864
	ds_read_b64_tr_b16 v[114:115], v200 offset:37376
	s_waitcnt lgkmcnt(14)
	v_mfma_f32_32x32x16_bf16 v[48:63], v[136:139], v[116:119], v[48:63]
	v_exp_f32_e32 v84, v84
	v_exp_f32_e32 v85, v85
	ds_read_b64_tr_b16 v[116:117], v200 offset:33792
	ds_read_b64_tr_b16 v[118:119], v200 offset:34304
	s_waitcnt lgkmcnt(14)
	v_mfma_f32_32x32x16_bf16 v[32:47], v[136:139], v[120:123], v[32:47]
	v_exp_f32_e32 v86, v86
	v_exp_f32_e32 v87, v87
	ds_read_b64_tr_b16 v[120:121], v200 offset:37888
	ds_read_b64_tr_b16 v[122:123], v200 offset:38400
	s_waitcnt lgkmcnt(14)
	v_mfma_f32_32x32x16_bf16 v[48:63], v[132:135], v[124:127], v[48:63]
	v_exp_f32_e32 v88, v88
	v_exp_f32_e32 v89, v89
	ds_read_b64_tr_b16 v[124:125], v200 offset:34816
	ds_read_b64_tr_b16 v[126:127], v200 offset:35328
	s_waitcnt lgkmcnt(14)
	v_mfma_f32_32x32x16_bf16 v[32:47], v[132:135], v[96:99], v[32:47]
	v_exp_f32_e32 v90, v90
	v_exp_f32_e32 v91, v91
	ds_read_b64_tr_b16 v[96:97], v200 offset:38912
	ds_read_b64_tr_b16 v[98:99], v200 offset:39424
	s_waitcnt lgkmcnt(14)
	v_mfma_f32_32x32x16_bf16 v[48:63], v[128:131], v[100:103], v[48:63]
	v_exp_f32_e32 v92, v92
	v_exp_f32_e32 v93, v93
	ds_read_b64_tr_b16 v[100:101], v200 offset:35840
	ds_read_b64_tr_b16 v[102:103], v200 offset:36352
	s_waitcnt lgkmcnt(14)
	v_mfma_f32_32x32x16_bf16 v[32:47], v[128:131], v[104:107], v[32:47]
	v_exp_f32_e32 v94, v94
	v_exp_f32_e32 v95, v95
	ds_read_b64_tr_b16 v[104:105], v200 offset:39936
	ds_read_b64_tr_b16 v[106:107], v200 offset:40448
	s_waitcnt lgkmcnt(14)
	v_mfma_f32_32x32x16_bf16 v[16:31], v[140:143], v[108:111], v[16:31]
	v_exp_f32_e32 v64, v64
	v_exp_f32_e32 v65, v65
	v_lshl_add_u32 v160, s61, 13, v239
	ds_read_b128 v[188:191], v160
	ds_read_b128 v[180:183], v160 offset:512
	s_waitcnt lgkmcnt(14)
	v_mfma_f32_32x32x16_bf16 v[0:15], v[140:143], v[112:115], v[0:15]
	v_exp_f32_e32 v66, v66
	v_exp_f32_e32 v67, v67
	ds_read_b128 v[184:187], v160 offset:2048
	ds_read_b128 v[176:179], v160 offset:2560
	s_waitcnt lgkmcnt(14)
	v_mfma_f32_32x32x16_bf16 v[16:31], v[136:139], v[116:119], v[16:31]
	v_exp_f32_e32 v68, v68
	v_exp_f32_e32 v69, v69
	s_waitcnt lgkmcnt(12)
	v_mfma_f32_32x32x16_bf16 v[0:15], v[136:139], v[120:123], v[0:15]
	v_exp_f32_e32 v70, v70
	v_exp_f32_e32 v71, v71
	ds_read_b128 v[172:175], v160 offset:4096
	ds_read_b128 v[168:171], v160 offset:4608
	s_waitcnt lgkmcnt(12)
	v_mfma_f32_32x32x16_bf16 v[16:31], v[132:135], v[124:127], v[16:31]
	v_exp_f32_e32 v72, v72
	v_exp_f32_e32 v73, v73
	ds_read_b128 v[164:167], v160 offset:6144
	ds_read_b128 v[160:163], v160 offset:6656
	s_waitcnt lgkmcnt(12)
	v_mfma_f32_32x32x16_bf16 v[0:15], v[132:135], v[96:99], v[0:15]
	v_exp_f32_e32 v74, v74
	v_exp_f32_e32 v75, v75
	s_waitcnt lgkmcnt(10)
	v_mfma_f32_32x32x16_bf16 v[16:31], v[128:131], v[100:103], v[16:31]
	v_exp_f32_e32 v76, v76
	v_exp_f32_e32 v77, v77
	s_waitcnt lgkmcnt(8)
	v_mfma_f32_32x32x16_bf16 v[0:15], v[128:131], v[104:107], v[0:15]
	v_exp_f32_e32 v78, v78
	v_exp_f32_e32 v79, v79
	s_add_i32 s3, s61, 1
	s_waitcnt vmcnt(3) lgkmcnt(0)
	s_barrier
	s_cmp_lg_u32 s61, 2
	s_cselect_b32 s62, s3, 0
	s_add_i32 s33, s63, 2
	v_lshl_add_u64 v[192:193], v[192:193], 0, s[12:13]
	v_lshl_add_u64 v[194:195], v[194:195], 0, s[12:13]
	s_cmp_ge_u32 s60, s42
	v_lshl_add_u64 v[96:97], v[218:219], 0, s[12:13]
	s_mov_b32 s36, s30
	s_cbranch_scc0 .LBB0_442
	s_add_i32 s3, s60, 1
	s_cmp_ge_u32 s3, s41
	v_readlane_b32 s65, v252, 9
	s_cbranch_scc1 .LBB0_477
